# two sample-slot epilogues: loads that sat behind write-through stores requested with the first batch (spatial sample step scalars; output-projection second tile planes)
# baseline (speedup 1.0000x reference)
.LBB11_1526:
	s_or_b64 exec, exec, s[10:11]
	v_readlane_b32 s0, v245, 25
	v_readlane_b32 s10, v248, 14
	v_readlane_b32 s1, v245, 26
	v_readlane_b32 s11, v248, 15
	v_mov_b32_e32 v0, v199
	v_mov_b32_e32 v2, v198
	s_andn2_b64 vcc, exec, s[0:1]
	s_barrier
	s_cbranch_vccnz .LBB11_1528
	s_load_dwordx8 s[12:19], s[10:11], 0x68
	s_load_dwordx4 s[20:23], s[10:11], 0x130
	s_lshl_b32 s60, s94, 10
	s_lshl_b64 s[0:1], s[60:61], 2
	v_lshlrev_b32_e32 v4, 2, v0
	s_waitcnt lgkmcnt(0)
	s_add_u32 s0, s18, s0
	s_addc_u32 s1, s19, s1
	s_lshl_b32 s60, s94, 11
	s_lshl_b64 s[6:7], s[60:61], 2
	s_add_u32 s8, s14, s6
	s_addc_u32 s9, s15, s7
	s_add_u32 s6, s12, s6
	s_addc_u32 s7, s13, s7
	s_add_u32 s12, s22, s44
	s_addc_u32 s13, s23, s43
	v_readlane_b32 s10, v245, 28
	v_readlane_b32 s11, v245, 29
	s_add_u32 s10, s22, s10
	v_ashrrev_i32_e32 v5, 31, v4
	s_addc_u32 s11, s23, s11
	v_lshlrev_b64 v[2:3], 1, v[4:5]
	v_lshl_add_u64 v[12:13], s[10:11], 0, v[2:3]
	s_mov_b32 s10, 0x1b401000
	v_add_co_u32_e32 v6, vcc, s10, v12
	v_readlane_b32 s10, v242, 24
	v_readlane_b32 s11, v242, 25
	s_add_u32 s10, s12, s10
	s_addc_u32 s11, s13, s11
	v_addc_co_u32_e32 v7, vcc, 0, v13, vcc
	global_load_dwordx2 v[16:17], v[6:7], off
	s_nop 0
	global_load_dwordx2 v[14:15], v211, s[10:11]
	v_lshlrev_b64 v[18:19], 2, v[4:5]
	v_lshl_add_u64 v[4:5], s[8:9], 0, v[18:19]
	v_lshl_add_u64 v[8:9], s[6:7], 0, v[18:19]
	global_load_dwordx4 v[4:7], v[4:5], off
	v_ashrrev_i32_e32 v20, 6, v0
	global_load_dwordx4 v[8:11], v[8:9], off
	v_lshlrev_b32_e32 v22, 7, v20
	v_ashrrev_i32_e32 v23, 31, v22
	v_lshl_add_u64 v[22:23], v[22:23], 2, s[0:1]
	s_mov_b32 s0, 0x1b400000
	v_add_co_u32_e32 v12, vcc, s0, v12
	s_lshl_b64 s[0:1], s[94:95], 20
	s_add_u32 s0, s20, s0
	s_addc_u32 s1, s21, s1
	v_readlane_b32 s6, v245, 27
	s_add_u32 s0, s0, s6
	s_addc_u32 s1, s1, 0
	s_lshl_b64 s[6:7], s[94:95], 19
	v_ashrrev_i32_e32 v21, 31, v20
	v_addc_co_u32_e32 v13, vcc, 0, v13, vcc
	v_lshl_add_u64 v[18:19], s[0:1], 0, v[18:19]
	s_add_u32 s0, s16, s6
	s_mov_b32 s1, 0x8900000
	v_lshlrev_b64 v[20:21], 16, v[20:21]
	v_add_co_u32_e32 v18, vcc, s1, v18
	s_addc_u32 s1, s17, s7
	v_lshl_add_u64 v[20:21], s[0:1], 0, v[20:21]
	s_mov_b32 s0, 0x3a000000
	v_addc_co_u32_e32 v19, vcc, 0, v19, vcc
	global_load_dwordx2 v[12:13], v[12:13], off
	global_load_dword v46, v[20:21], off
	global_load_dword v47, v[22:23], off
	s_waitcnt vmcnt(6)
	v_lshlrev_b32_e32 v24, 16, v16
	s_waitcnt vmcnt(5)
	v_pk_mul_f32 v[14:15], v[14:15], s[0:1] op_sel_hi:[1,0]
	v_readlane_b32 s0, v245, 30
	v_fma_f32 v0, -v14, v14, v15
	v_max_f32_e32 v0, 0, v0
	v_add_f32_e32 v0, 0x358637bd, v0
	v_cmp_gt_f32_e32 vcc, s77, v0
	v_mul_f32_e32 v25, 0x4b800000, v0
	v_and_b32_e32 v15, 0xffff0000, v16
	v_cndmask_b32_e32 v0, v0, v25, vcc
	v_rsq_f32_e32 v0, v0
	v_lshlrev_b32_e32 v16, 16, v17
	v_and_b32_e32 v17, 0xffff0000, v17
	v_sub_f32_e32 v17, v17, v14
	v_sub_f32_e32 v16, v16, v14
	v_sub_f32_e32 v15, v15, v14
	v_sub_f32_e32 v14, v24, v14
	v_mul_f32_e32 v24, 0x45800000, v0
	v_cndmask_b32_e32 v0, v0, v24, vcc
	v_pk_mul_f32 v[14:15], v[14:15], v[0:1] op_sel_hi:[1,0]
	v_pk_mul_f32 v[16:17], v[16:17], v[0:1] op_sel_hi:[1,0]
	s_waitcnt vmcnt(3)
	v_pk_fma_f32 v[4:5], v[8:9], v[14:15], v[4:5]
	v_pk_fma_f32 v[6:7], v[10:11], v[16:17], v[6:7]
	global_store_dwordx4 v[18:19], v[4:7], off sc1
	v_readlane_b32 s1, v245, 31
	s_add_u32 s0, s22, s0
	s_addc_u32 s1, s23, s1
	v_lshl_add_u64 v[2:3], s[0:1], 0, v[2:3]
	v_add_co_u32_e32 v2, vcc, 0x23600000, v2
	s_waitcnt vmcnt(3)
	v_lshlrev_b32_e32 v10, 16, v12
	v_and_b32_e32 v11, 0xffff0000, v12
	v_lshlrev_b32_e32 v12, 16, v13
	v_and_b32_e32 v13, 0xffff0000, v13
	v_addc_co_u32_e32 v3, vcc, 0, v3, vcc
	s_waitcnt vmcnt(1)
	v_mov_b32_e32 v0, v46
	v_mov_b32_e32 v8, v47
	v_pk_fma_f32 v[4:5], v[0:1], v[4:5], v[8:9] op_sel_hi:[0,1,0]
	v_pk_fma_f32 v[6:7], v[0:1], v[6:7], v[8:9] op_sel_hi:[0,1,0]
	v_pk_mul_f32 v[4:5], v[4:5], v[10:11]
	v_pk_mul_f32 v[6:7], v[6:7], v[12:13]
	v_cvt_pk_bf16_f32 v4, v4, v5
	s_nop 0
	v_cvt_pk_bf16_f32 v5, v6, v7
	global_store_dwordx2 v[2:3], v[4:5], off sc1

.LBB11_2462:
	s_or_b64 exec, exec, s[30:31]
	s_waitcnt lgkmcnt(0)
	s_waitcnt lgkmcnt(0)
	s_barrier
	ds_read_b128 v[108:111], v106
	ds_read_b128 v[112:115], v106 offset:33024
	v_readlane_b32 s0, v245, 5
	s_andn2_b64 vcc, exec, s[2:3]
	s_waitcnt vmcnt(7) lgkmcnt(1)
	v_mfma_f32_16x16x32_bf16 v[108:111], v[108:111], v[62:65], 0
	v_add_u32_e32 v0, s0, v86
	s_waitcnt lgkmcnt(0)
	v_mfma_f32_16x16x32_bf16 v[62:65], v[112:115], v[62:65], 0
	ds_read_b128 v[112:115], v106 offset:64
	s_waitcnt vmcnt(6) lgkmcnt(0)
	v_mfma_f32_16x16x32_bf16 v[108:111], v[112:115], v[58:61], v[108:111]
	ds_read_b128 v[112:115], v106 offset:33088
	s_waitcnt lgkmcnt(0)
	v_mfma_f32_16x16x32_bf16 v[58:61], v[112:115], v[58:61], v[62:65]
	s_nop 2
	ds_read_b128 v[62:65], v106 offset:128
	s_waitcnt vmcnt(5) lgkmcnt(0)
	v_mfma_f32_16x16x32_bf16 v[62:65], v[62:65], v[54:57], v[108:111]
	s_nop 2
	ds_read_b128 v[108:111], v106 offset:33152
	s_waitcnt lgkmcnt(0)
	v_mfma_f32_16x16x32_bf16 v[54:57], v[108:111], v[54:57], v[58:61]
	s_nop 2
	ds_read_b128 v[58:61], v106 offset:192
	s_waitcnt vmcnt(4) lgkmcnt(0)
	v_mfma_f32_16x16x32_bf16 v[58:61], v[58:61], v[50:53], v[62:65]
	s_nop 2
	ds_read_b128 v[62:65], v106 offset:33216
	s_waitcnt lgkmcnt(0)
	v_mfma_f32_16x16x32_bf16 v[50:53], v[62:65], v[50:53], v[54:57]
	s_nop 2
	ds_read_b128 v[54:57], v106 offset:256
	s_waitcnt vmcnt(3) lgkmcnt(0)
	v_mfma_f32_16x16x32_bf16 v[54:57], v[54:57], v[46:49], v[58:61]
	s_nop 2
	ds_read_b128 v[58:61], v106 offset:33280
	s_waitcnt lgkmcnt(0)
	v_mfma_f32_16x16x32_bf16 v[46:49], v[58:61], v[46:49], v[50:53]
	s_nop 2
	ds_read_b128 v[50:53], v106 offset:320
	s_waitcnt vmcnt(2) lgkmcnt(0)
	v_mfma_f32_16x16x32_bf16 v[50:53], v[50:53], v[42:45], v[54:57]
	s_nop 2
	ds_read_b128 v[54:57], v106 offset:33344
	s_waitcnt lgkmcnt(0)
	v_mfma_f32_16x16x32_bf16 v[42:45], v[54:57], v[42:45], v[46:49]
	s_nop 2
	ds_read_b128 v[46:49], v106 offset:384
	s_waitcnt vmcnt(1) lgkmcnt(0)
	v_mfma_f32_16x16x32_bf16 v[46:49], v[46:49], v[38:41], v[50:53]
	s_nop 2
	ds_read_b128 v[50:53], v106 offset:33408
	s_waitcnt lgkmcnt(0)
	v_mfma_f32_16x16x32_bf16 v[42:45], v[50:53], v[38:41], v[42:45]
	ds_read_b128 v[38:41], v106 offset:448
	s_waitcnt vmcnt(0) lgkmcnt(0)
	v_mfma_f32_16x16x32_bf16 v[38:41], v[38:41], v[34:37], v[46:49]
	s_nop 2
	ds_read_b128 v[46:49], v106 offset:33472
	s_waitcnt lgkmcnt(0)
	v_mfma_f32_16x16x32_bf16 v[34:37], v[46:49], v[34:37], v[42:45]
	s_nop 1
	ds_write_b128 v0, v[38:41]
	s_nop 4
	ds_write_b128 v0, v[34:37] offset:1024
	s_waitcnt lgkmcnt(0)
	s_waitcnt lgkmcnt(0)
	s_barrier
	s_cbranch_vccnz .LBB11_2429
	v_readlane_b32 s0, v245, 6
	s_nop 1
	v_add_u32_e32 v0, s0, v86
	ds_read_b128 v[42:45], v0 offset:4096
	s_lshl_b32 s0, s9, 17
	s_waitcnt lgkmcnt(0)
	v_pk_add_f32 v[44:45], v[40:41], v[44:45]
	v_pk_add_f32 v[42:43], v[38:39], v[42:43]
	ds_read_b128 v[38:41], v0 offset:5120
	s_waitcnt lgkmcnt(0)
	v_pk_add_f32 v[40:41], v[36:37], v[40:41]
	v_pk_add_f32 v[38:39], v[34:35], v[38:39]
	ds_read_b128 v[34:37], v0 offset:8192
	s_waitcnt lgkmcnt(0)
	v_pk_add_f32 v[44:45], v[44:45], v[36:37]
	v_pk_add_f32 v[42:43], v[42:43], v[34:35]
	ds_read_b128 v[34:37], v0 offset:9216
	s_waitcnt lgkmcnt(0)
	v_pk_add_f32 v[40:41], v[40:41], v[36:37]
	v_pk_add_f32 v[46:47], v[38:39], v[34:35]
	ds_read_b128 v[34:37], v0 offset:12288
	s_waitcnt lgkmcnt(0)
	v_pk_add_f32 v[44:45], v[44:45], v[36:37]
	ds_read_b128 v[36:39], v0 offset:13312
	v_pk_add_f32 v[42:43], v[42:43], v[34:35]
	v_subrev_u32_e32 v0, s0, v97
	s_waitcnt lgkmcnt(0)
	v_pk_add_f32 v[34:35], v[40:41], v[38:39]
	v_add_u32_e32 v38, s34, v87
	v_lshlrev_b64 v[40:41], 1, v[0:1]
	v_ashrrev_i32_e32 v39, 31, v38
	v_pk_add_f32 v[36:37], v[46:47], v[36:37]
	v_lshl_add_u64 v[46:47], s[66:67], 0, v[40:41]
	v_lshlrev_b64 v[48:49], 1, v[38:39]
	v_lshl_add_u64 v[38:39], v[46:47], 0, v[48:49]
	v_lshl_add_u64 v[40:41], s[64:65], 0, v[40:41]
	v_lshl_add_u64 v[40:41], v[40:41], 0, v[48:49]
	global_load_dwordx2 v[46:47], v[38:39], off
	global_load_dwordx2 v[48:49], v[40:41], off
	global_load_dwordx2 v[54:55], v[38:39], off offset:32
	global_load_dwordx2 v[56:57], v[40:41], off offset:32
	s_waitcnt vmcnt(3)
	v_lshlrev_b32_e32 v50, 16, v46
	v_and_b32_e32 v51, 0xffff0000, v46
	s_waitcnt vmcnt(2)
	v_lshlrev_b32_e32 v52, 16, v48
	v_and_b32_e32 v53, 0xffff0000, v48
	v_lshlrev_b32_e32 v46, 16, v47
	v_and_b32_e32 v47, 0xffff0000, v47
	v_lshlrev_b32_e32 v48, 16, v49
	v_and_b32_e32 v49, 0xffff0000, v49
	v_pk_add_f32 v[50:51], v[50:51], v[52:53]
	v_pk_add_f32 v[46:47], v[46:47], v[48:49]
	v_pk_add_f32 v[42:43], v[42:43], v[50:51]
	v_pk_add_f32 v[44:45], v[44:45], v[46:47]
	v_cvt_pk_bf16_f32 v46, v42, v43
	s_nop 0
	v_cvt_pk_bf16_f32 v47, v44, v45
	v_lshlrev_b32_e32 v48, 16, v46
	v_and_b32_e32 v49, 0xffff0000, v46
	v_lshlrev_b32_e32 v50, 16, v47
	v_and_b32_e32 v51, 0xffff0000, v47
	v_sub_f32_e32 v0, v44, v50
	v_sub_f32_e32 v44, v45, v51
	v_sub_f32_e32 v42, v42, v48
	v_sub_f32_e32 v43, v43, v49
	v_cvt_pk_bf16_f32 v42, v42, v43
	v_cvt_pk_bf16_f32 v43, v0, v44
	global_store_dwordx2 v[38:39], v[46:47], off sc1
	global_store_dwordx2 v[40:41], v[42:43], off sc1
	v_lshlrev_b32_e32 v44, 16, v42
	v_and_b32_e32 v45, 0xffff0000, v42
	v_lshlrev_b32_e32 v52, 16, v43
	v_and_b32_e32 v53, 0xffff0000, v43
	v_pk_add_f32 v[50:51], v[50:51], v[52:53]
	v_pk_add_f32 v[44:45], v[48:49], v[44:45]
	v_mul_f32_e32 v42, v51, v51
	v_mul_f32_e32 v0, v45, v45
	v_fmac_f32_e32 v0, v44, v44
	v_fmac_f32_e32 v42, v50, v50
	v_add_f32_e32 v0, v0, v42
	s_waitcnt vmcnt(3)
	v_mov_b32_e32 v42, v54
	v_mov_b32_e32 v43, v55
	v_lshlrev_b32_e32 v46, 16, v42
	v_and_b32_e32 v47, 0xffff0000, v42
	s_waitcnt vmcnt(2)
	v_mov_b32_e32 v44, v56
	v_mov_b32_e32 v45, v57
	v_lshlrev_b32_e32 v48, 16, v44
	v_and_b32_e32 v49, 0xffff0000, v44
	v_lshlrev_b32_e32 v42, 16, v43
	v_and_b32_e32 v43, 0xffff0000, v43
	v_lshlrev_b32_e32 v44, 16, v45
	v_and_b32_e32 v45, 0xffff0000, v45
	v_pk_add_f32 v[46:47], v[46:47], v[48:49]
	v_pk_add_f32 v[42:43], v[42:43], v[44:45]
	v_pk_add_f32 v[36:37], v[36:37], v[46:47]
	v_pk_add_f32 v[34:35], v[34:35], v[42:43]
	v_cvt_pk_bf16_f32 v42, v36, v37
	s_nop 0
	v_cvt_pk_bf16_f32 v43, v34, v35
	v_lshlrev_b32_e32 v44, 16, v42
	v_and_b32_e32 v45, 0xffff0000, v42
	v_lshlrev_b32_e32 v46, 16, v43
	v_and_b32_e32 v47, 0xffff0000, v43
	v_sub_f32_e32 v48, v34, v46
	v_sub_f32_e32 v35, v35, v47
	v_sub_f32_e32 v34, v36, v44
	v_sub_f32_e32 v36, v37, v45
	v_cvt_pk_bf16_f32 v34, v34, v36
	v_cvt_pk_bf16_f32 v35, v48, v35
	global_store_dwordx2 v[38:39], v[42:43], off offset:32 sc1
	global_store_dwordx2 v[40:41], v[34:35], off offset:32 sc1
	v_lshlrev_b32_e32 v36, 16, v34
	v_and_b32_e32 v37, 0xffff0000, v34
	v_lshlrev_b32_e32 v48, 16, v35
	v_and_b32_e32 v49, 0xffff0000, v35
	v_pk_add_f32 v[46:47], v[46:47], v[48:49]
	v_pk_add_f32 v[36:37], v[44:45], v[36:37]
	v_mul_f32_e32 v35, v47, v47
	v_mul_f32_e32 v34, v37, v37
	v_fmac_f32_e32 v34, v36, v36
	v_fmac_f32_e32 v35, v46, v46
	v_add_f32_e32 v34, v34, v35
	v_add_f32_e32 v0, v0, v34
	ds_bpermute_b32 v34, v204, v0
	s_waitcnt lgkmcnt(0)
	v_add_f32_e32 v34, v0, v34
	ds_bpermute_b32 v35, v205, v34
	s_and_saveexec_b64 s[30:31], s[10:11]
	s_cbranch_execz .LBB11_2428
	v_add_u32_e32 v0, 0x4000, v84
	v_lshl_add_u64 v[36:37], v[0:1], 2, s[28:29]
	s_waitcnt lgkmcnt(0)
	v_add_f32_e32 v0, v34, v35
	global_atomic_add_f32 v[36:37], v0, off
	s_branch .LBB11_2428
